# X2 prompt: Q fragment loads issued behind the coalesced K/V staging loads
# speedup vs baseline: 1.0040x; 1.0040x over previous
; __device__ __forceinline__ void xattn_prompt_item(const bf16_t* xq, const bf16_t* xq1, const bf16_t* memkv, const bf16_t* memvt, bf16_t* xo, int l, int it, int lane) {
;     const int h = it & 3, qt = it >> 2, b = qt >> 8;
;     const int l15 = lane & 15, g = lane >> 4;
;     const size_t tok = (size_t)qt * 16 + l15;
;     bf16x8 qf[4];
; #pragma unroll
;     for (int ks = 0; ks < 4; ++ks) {
;         const u32x4 a = *(const u32x4*)(xq + tok * 512 + h * 128 + 32 * ks + 8 * g), c = *(const u32x4*)(xq1 + tok * 512 + h * 128 + 32 * ks + 8 * g);
.Lxp_pair:
	s_and_b32 s7, s6, 3
	s_lshr_b32 s4, s6, 2
	s_lshr_b32 s5, s4, 5
	s_lshl_b32 s4, s4, 3
	s_ashr_i32 s16, s27, 6
	s_add_i32 s4, s4, s16
	s_lshl_b32 s80, s7, 8
	s_lshl_b32 s4, s4, 14
	s_add_i32 s4, s4, s80
	s_add_u32 s22, s10, s4
	s_addc_u32 s23, s11, 0
	s_add_u32 s24, s12, s4
	s_addc_u32 s25, s13, 0
	s_cmp_lg_u32 s28, 0
	s_cbranch_scc1 .Lxp_nostage
; #define MFMA16(a, b, c) __builtin_amdgcn_mfma_f32_16x16x32_bf16((a), (b), (c), 0, 0, 0)
; __device__ __forceinline__ float bf_lo(unsigned w) { return __uint_as_float(w << 16); }
; __device__ __forceinline__ float bf_hi(unsigned w) { return __uint_as_float(w & 0xffff0000u); }
; __device__ __forceinline__ void xattn_prompt_item(const bf16_t* xq, const bf16_t* xq1, const bf16_t* memkv, const bf16_t* memvt, bf16_t* xo, int l, int it, int lane) {
;     ...
;     for (int ks = 0; ks < 4; ++ks) {
;         const u32x4 a = *(const u32x4*)(xq + tok * 512 + h * 128 + 32 * ks + 8 * g), c = *(const u32x4*)(xq1 + tok * 512 + h * 128 + 32 * ks + 8 * g);
;         u32x4 w; w.x = pk2(bf_lo(a.x) + bf_lo(c.x), bf_hi(a.x) + bf_hi(c.x)); w.y = pk2(bf_lo(a.y) + bf_lo(c.y), bf_hi(a.y) + bf_hi(c.y));
;         w.z = pk2(bf_lo(a.z) + bf_lo(c.z), bf_hi(a.z) + bf_hi(c.z)); w.w = pk2(bf_lo(a.w) + bf_lo(c.w), bf_hi(a.w) + bf_hi(c.w));
;         qf[ks] = as_bf16x8(w);
;     ...
;         const bf16_t* kp = memkv + ((size_t)b * 256 + 16 * kt + l15) * 4096 + l * 1024 + h * 128 + 8 * g;
;         f32x4 a = {0.f, 0.f, 0.f, 0.f};
; #pragma unroll
;         for (int ks = 0; ks < 4; ++ks) a = MFMA16(*(const bf16x8*)(kp + 32 * ks), qf[ks], a);
;         a = a * 0.08838834764831845f;
;         sc[kt] = a; mx = fmaxf(fmaxf(mx, fmaxf(a[0], a[1])), fmaxf(a[2], a[3]));
;     }
;     mx = fmaxf(mx, __shfl_xor(mx, 16)); mx = fmaxf(mx, __shfl_xor(mx, 32));
;     float sum = 0.f;
; #pragma unroll
;     for (int kt = 0; kt < 16; ++kt)
; #pragma unroll
;         for (int j = 0; j < 4; ++j) { const float p = __expf(sc[kt][j] - mx); sc[kt][j] = p; sum += p; }
;     sum += __shfl_xor(sum, 16); sum += __shfl_xor(sum, 32);
;     const float inv = 1.0f / sum;
;     f32x4 o[8];
; #pragma unroll
;     for (int mi = 0; mi < 8; ++mi) o[mi] = (f32x4){0.f, 0.f, 0.f, 0.f};
; #pragma unroll
;     for (int u = 0; u < 8; ++u) {
;         u32x4 pw; pw.x = pk2(sc[2 * u][0] * inv, sc[2 * u][1] * inv); pw.y = pk2(sc[2 * u][2] * inv, sc[2 * u][3] * inv);
;         pw.z = pk2(sc[2 * u + 1][0] * inv, sc[2 * u + 1][1] * inv); pw.w = pk2(sc[2 * u + 1][2] * inv, sc[2 * u + 1][3] * inv);
;         const bf16x8 pb = as_bf16x8(pw);
;         const int pos0 = 32 * u + 4 * g;
; #pragma unroll
;         for (int mi = 0; mi < 8; ++mi) {
;             const bf16_t* vp = memvt + ((size_t)((l * 2 + b) * 512 + h * 128 + 16 * mi + l15)) * 256 + pos0;
	v_readlane_b32 s18, v254, 42
	v_readlane_b32 s19, v254, 43
	v_readlane_b32 s20, v254, 38
	s_nop 0
	s_lshl_b32 s21, s20, 11
	s_add_i32 s21, s21, s80
	s_lshl_b32 s16, s5, 21
	s_add_i32 s21, s21, s16
	s_add_u32 s16, s18, 0x28c28000
	s_addc_u32 s17, s19, 0
	s_add_u32 s16, s16, s21
	s_addc_u32 s17, s17, 0
	s_lshl_b32 s20, s20, 1
	s_add_i32 s20, s20, s5
	s_lshl_b32 s20, s20, 18
	s_lshl_b32 s21, s7, 16
	s_add_i32 s21, s21, s20
	s_add_u32 s20, s18, 0x29028000
	s_addc_u32 s19, s19, 0
	s_add_u32 s20, s20, s21
	s_addc_u32 s21, s19, 0
	s_add_u32 s4, s14, s4
	s_addc_u32 s5, s15, 0
	global_load_dwordx4 v[146:149], v58, s[16:17]
	s_add_u32 s16, s16, 0x40000
	s_addc_u32 s17, s17, 0
	global_load_dwordx4 v[150:153], v58, s[16:17]
	s_add_u32 s16, s16, 0x40000
	s_addc_u32 s17, s17, 0
	global_load_dwordx4 v[154:157], v58, s[16:17]
	s_add_u32 s16, s16, 0x40000
	s_addc_u32 s17, s17, 0
	global_load_dwordx4 v[158:161], v58, s[16:17]
	s_add_u32 s16, s16, 0x40000
	s_addc_u32 s17, s17, 0
	global_load_dwordx4 v[162:165], v58, s[16:17]
	s_add_u32 s16, s16, 0x40000
	s_addc_u32 s17, s17, 0
	global_load_dwordx4 v[166:169], v58, s[16:17]
	s_add_u32 s16, s16, 0x40000
	s_addc_u32 s17, s17, 0
	global_load_dwordx4 v[170:173], v58, s[16:17]
	s_add_u32 s16, s16, 0x40000
	s_addc_u32 s17, s17, 0
	global_load_dwordx4 v[174:177], v58, s[16:17]
	global_load_dwordx4 v[178:181], v60, s[20:21]
	s_add_u32 s20, s20, 0x2000
	s_addc_u32 s21, s21, 0
	global_load_dwordx4 v[182:185], v60, s[20:21]
	s_add_u32 s20, s20, 0x2000
	s_addc_u32 s21, s21, 0
	global_load_dwordx4 v[186:189], v60, s[20:21]
	s_add_u32 s20, s20, 0x2000
	s_addc_u32 s21, s21, 0
	global_load_dwordx4 v[190:193], v60, s[20:21]
	s_add_u32 s20, s20, 0x2000
	s_addc_u32 s21, s21, 0
	global_load_dwordx4 v[194:197], v60, s[20:21]
	s_add_u32 s20, s20, 0x2000
	s_addc_u32 s21, s21, 0
	global_load_dwordx4 v[198:201], v60, s[20:21]
	s_add_u32 s20, s20, 0x2000
	s_addc_u32 s21, s21, 0
	global_load_dwordx4 v[202:205], v60, s[20:21]
	s_add_u32 s20, s20, 0x2000
	s_addc_u32 s21, s21, 0
	global_load_dwordx4 v[206:209], v60, s[20:21]
	global_load_dwordx4 v[26:29], v2, s[22:23] offset:0
	global_load_dwordx4 v[30:33], v2, s[22:23] offset:64
	global_load_dwordx4 v[34:37], v2, s[22:23] offset:128
	global_load_dwordx4 v[38:41], v2, s[22:23] offset:192
	global_load_dwordx4 v[42:45], v2, s[24:25] offset:0
	global_load_dwordx4 v[46:49], v2, s[24:25] offset:64
	global_load_dwordx4 v[50:53], v2, s[24:25] offset:128
	global_load_dwordx4 v[54:57], v2, s[24:25] offset:192
	s_waitcnt vmcnt(23)
	ds_write_b128 v59, v[146:149] offset:0
	s_waitcnt vmcnt(22)
	ds_write_b128 v59, v[150:153] offset:8704
	s_waitcnt vmcnt(21)
	ds_write_b128 v59, v[154:157] offset:17408
	s_waitcnt vmcnt(20)
	ds_write_b128 v59, v[158:161] offset:26112
	s_waitcnt vmcnt(19)
	ds_write_b128 v59, v[162:165] offset:34816
	s_waitcnt vmcnt(18)
	ds_write_b128 v59, v[166:169] offset:43520
	s_waitcnt vmcnt(17)
	ds_write_b128 v59, v[170:173] offset:52224
	s_waitcnt vmcnt(16)
	ds_write_b128 v59, v[174:177] offset:60928
	s_waitcnt vmcnt(15)
	ds_write_b128 v61, v[178:181] offset:0
	s_waitcnt vmcnt(14)
	ds_write_b128 v61, v[182:185] offset:8448
	s_waitcnt vmcnt(13)
	ds_write_b128 v61, v[186:189] offset:16896
	s_waitcnt vmcnt(12)
	ds_write_b128 v61, v[190:193] offset:25344
	s_waitcnt vmcnt(11)
	ds_write_b128 v61, v[194:197] offset:33792
	s_waitcnt vmcnt(10)
	ds_write_b128 v61, v[198:201] offset:42240
	s_waitcnt vmcnt(9)
	ds_write_b128 v61, v[202:205] offset:50688
	s_waitcnt vmcnt(8)
	ds_write_b128 v61, v[206:209] offset:59136
	s_waitcnt vmcnt(0)
	v_lshlrev_b32_e32 v8, 16, v26
	v_and_b32_e32 v9, 0xffff0000, v26
	v_lshlrev_b32_e32 v136, 16, v42
	v_and_b32_e32 v137, 0xffff0000, v42
	v_pk_add_f32 v[8:9], v[8:9], v[136:137]
	v_cvt_pk_bf16_f32 v10, v8, v9
	v_lshlrev_b32_e32 v8, 16, v27
	v_and_b32_e32 v9, 0xffff0000, v27
	v_lshlrev_b32_e32 v136, 16, v43
	v_and_b32_e32 v137, 0xffff0000, v43
	v_pk_add_f32 v[8:9], v[8:9], v[136:137]
	v_cvt_pk_bf16_f32 v11, v8, v9
	v_lshlrev_b32_e32 v8, 16, v28
	v_and_b32_e32 v9, 0xffff0000, v28
	v_lshlrev_b32_e32 v136, 16, v44
	v_and_b32_e32 v137, 0xffff0000, v44
	v_pk_add_f32 v[8:9], v[8:9], v[136:137]
	v_cvt_pk_bf16_f32 v12, v8, v9
	v_lshlrev_b32_e32 v8, 16, v29
	v_and_b32_e32 v9, 0xffff0000, v29
	v_lshlrev_b32_e32 v136, 16, v45
	v_and_b32_e32 v137, 0xffff0000, v45
	v_pk_add_f32 v[8:9], v[8:9], v[136:137]
	v_cvt_pk_bf16_f32 v13, v8, v9
	v_lshlrev_b32_e32 v8, 16, v30
	v_and_b32_e32 v9, 0xffff0000, v30
	v_lshlrev_b32_e32 v136, 16, v46
	v_and_b32_e32 v137, 0xffff0000, v46
	v_pk_add_f32 v[8:9], v[8:9], v[136:137]
	v_cvt_pk_bf16_f32 v14, v8, v9
	v_lshlrev_b32_e32 v8, 16, v31
	v_and_b32_e32 v9, 0xffff0000, v31
	v_lshlrev_b32_e32 v136, 16, v47
	v_and_b32_e32 v137, 0xffff0000, v47
	v_pk_add_f32 v[8:9], v[8:9], v[136:137]
	v_cvt_pk_bf16_f32 v15, v8, v9
	v_lshlrev_b32_e32 v8, 16, v32
	v_and_b32_e32 v9, 0xffff0000, v32
	v_lshlrev_b32_e32 v136, 16, v48
	v_and_b32_e32 v137, 0xffff0000, v48
	v_pk_add_f32 v[8:9], v[8:9], v[136:137]
	v_cvt_pk_bf16_f32 v16, v8, v9
	v_lshlrev_b32_e32 v8, 16, v33
	v_and_b32_e32 v9, 0xffff0000, v33
	v_lshlrev_b32_e32 v136, 16, v49
	v_and_b32_e32 v137, 0xffff0000, v49
	v_pk_add_f32 v[8:9], v[8:9], v[136:137]
	v_cvt_pk_bf16_f32 v17, v8, v9
	v_lshlrev_b32_e32 v8, 16, v34
	v_and_b32_e32 v9, 0xffff0000, v34
	v_lshlrev_b32_e32 v136, 16, v50
	v_and_b32_e32 v137, 0xffff0000, v50
	v_pk_add_f32 v[8:9], v[8:9], v[136:137]
	v_cvt_pk_bf16_f32 v18, v8, v9
	v_lshlrev_b32_e32 v8, 16, v35
	v_and_b32_e32 v9, 0xffff0000, v35
	v_lshlrev_b32_e32 v136, 16, v51
	v_and_b32_e32 v137, 0xffff0000, v51
	v_pk_add_f32 v[8:9], v[8:9], v[136:137]
	v_cvt_pk_bf16_f32 v19, v8, v9
	v_lshlrev_b32_e32 v8, 16, v36
	v_and_b32_e32 v9, 0xffff0000, v36
	v_lshlrev_b32_e32 v136, 16, v52
	v_and_b32_e32 v137, 0xffff0000, v52
	v_pk_add_f32 v[8:9], v[8:9], v[136:137]
	v_cvt_pk_bf16_f32 v20, v8, v9
	v_lshlrev_b32_e32 v8, 16, v37
	v_and_b32_e32 v9, 0xffff0000, v37
	v_lshlrev_b32_e32 v136, 16, v53
	v_and_b32_e32 v137, 0xffff0000, v53
	v_pk_add_f32 v[8:9], v[8:9], v[136:137]
	v_cvt_pk_bf16_f32 v21, v8, v9
	v_lshlrev_b32_e32 v8, 16, v38
	v_and_b32_e32 v9, 0xffff0000, v38
	v_lshlrev_b32_e32 v136, 16, v54
	v_and_b32_e32 v137, 0xffff0000, v54
	v_pk_add_f32 v[8:9], v[8:9], v[136:137]
	v_cvt_pk_bf16_f32 v22, v8, v9
	v_lshlrev_b32_e32 v8, 16, v39
	v_and_b32_e32 v9, 0xffff0000, v39
	v_lshlrev_b32_e32 v136, 16, v55
	v_and_b32_e32 v137, 0xffff0000, v55
	v_pk_add_f32 v[8:9], v[8:9], v[136:137]
	v_cvt_pk_bf16_f32 v23, v8, v9
	v_lshlrev_b32_e32 v8, 16, v40
	v_and_b32_e32 v9, 0xffff0000, v40
	v_lshlrev_b32_e32 v136, 16, v56
	v_and_b32_e32 v137, 0xffff0000, v56
	v_pk_add_f32 v[8:9], v[8:9], v[136:137]
	v_cvt_pk_bf16_f32 v24, v8, v9
	v_lshlrev_b32_e32 v8, 16, v41
	v_and_b32_e32 v9, 0xffff0000, v41
	v_lshlrev_b32_e32 v136, 16, v57
	v_and_b32_e32 v137, 0xffff0000, v57
	v_pk_add_f32 v[8:9], v[8:9], v[136:137]
	v_cvt_pk_bf16_f32 v25, v8, v9
	s_waitcnt lgkmcnt(0)
	s_barrier
	s_branch .Lxp_go
